# group-B release issued right after the last fragment read (delta) / without the redundant LDS wait (GLA); loader polls without sleep
# speedup vs baseline: 1.0063x; 1.0063x over previous
; #define LAS __attribute__((address_space(3)))
; template <bool SLEEP = false> __device__ __forceinline__ bool lds_wait_ge(volatile LAS unsigned* w, unsigned need, volatile LAS unsigned* abortw) {
;     unsigned sp = 0; bool ok = true;
;     while (*w < need) { if (SLEEP) __builtin_amdgcn_s_sleep(1); if ((++sp & 1023u) == 0u) { if (*abortw != 0u) { ok = false; break; } if (sp > (1u << 22)) { *abortw = 1u; ok = false; break; } } }
;     __builtin_amdgcn_fence(__ATOMIC_ACQUIRE, "workgroup");
; __device__ __forceinline__ void scan_loader(const P& p, int id, int role, LAS unsigned char* ldsw, int lane) {
;     ...
;         if (!lds_wait_ge<true>(FL + (role < 2 ? 3 : 4), (unsigned)n, FL + 5)) break;
.LBB0_1451:
	s_and_b32 s10, s40, 0x3ff
	s_mov_b64 s[8:9], -1
	s_cmp_lg_u32 s10, 0
	s_mov_b64 s[14:15], -1
	s_cbranch_scc0 .LBB0_1454
	s_mov_b64 s[12:13], 0
	s_and_b64 vcc, exec, s[14:15]
	s_cbranch_vccz .LBB0_1450

; #define LAS __attribute__((address_space(3)))
; __device__ __forceinline__ f32x16 mma32(bf16x8 a, bf16x8 b, f32x16 c) { return __builtin_amdgcn_mfma_f32_32x32x16_bf16(a, b, c, 0, 0, 0); }
; __device__ __forceinline__ int acc_row(int reg, int hh) { return (reg & 3) + 8 * (reg >> 2) + 4 * hh; }
; __device__ __forceinline__ void delta_scan_task(const P& p, int l, int s, int h, int sl, LAS unsigned char* ldsw, int lane) {
;     ...
;         bf16x8 ub[4];
; #pragma unroll
;         for (int ks = 0; ks < 4; ++ks) ub[ks] = *(const LAS bf16x8*)(UT + r * 72 + 16 * ks + 8 * hh);
; #pragma unroll
;         for (int ti = 0; ti < 2; ++ti) {
; #pragma unroll
;             for (int ks = 0; ks < 4; ++ks) o[ti] = mma32(FRAG16(bufB, ti * 4 + ks, lane), ub[ks], o[ti]);
; #pragma unroll
;             for (int reg = 0; reg < 16; ++reg) p.OCRAW[(size_t)(r0 + 32 * ti + acc_row(reg, hh)) * 1024 + h * 128 + 32 * sl + r] = o[ti][reg];
;         }
; #pragma unroll
;         for (int d = 0; d < 4; ++d) {
; #pragma unroll
;             for (int reg = 0; reg < 16; ++reg) S[d][reg] *= dec;
; #pragma unroll
;             for (int ks = 0; ks < 4; ++ks) S[d] = mma32(FRAG16(bufB, 8 + d * 4 + ks, lane), ub[ks], S[d]);
;         }
.LBB0_1515:
	s_waitcnt lgkmcnt(0)
	v_add_u32_e32 v172, v195, v148
	v_lshl_add_u32 v162, s7, 18, v149
	ds_read_b128 v[110:113], v172 offset:8704
	ds_read_b128 v[106:109], v172 offset:8736
	ds_read_b128 v[102:105], v172 offset:8768
	ds_read_b128 v[98:101], v172 offset:8800
	ds_read_b128 v[236:239], v209 offset:57344
	ds_read_b128 v[240:243], v209 offset:58368
	ds_read_b128 v[244:247], v209 offset:59392
	ds_read_b128 v[168:171], v209 offset:60416
	ds_read_b128 v[232:235], v209 offset:61440
	ds_read_b128 v[118:121], v209 offset:62464
	s_waitcnt lgkmcnt(5)
	v_mfma_f32_32x32x16_bf16 v[82:97], v[236:239], v[110:113], v[82:97]
	v_mul_f32_e64 v64, v64, s6
	v_mul_f32_e64 v65, v65, s6
	v_mul_f32_e64 v62, v62, s6
	v_mul_f32_e64 v63, v63, s6
	v_pk_mul_f32 v[60:61], v[60:61], s[6:7] op_sel_hi:[1,0]
	v_pk_mul_f32 v[58:59], v[58:59], s[6:7] op_sel_hi:[1,0]
	ds_read_b128 v[122:125], v209 offset:63488
	s_waitcnt lgkmcnt(5)
	v_mfma_f32_32x32x16_bf16 v[82:97], v[240:243], v[106:109], v[82:97]
	v_pk_mul_f32 v[56:57], v[56:57], s[6:7] op_sel_hi:[1,0]
	v_pk_mul_f32 v[54:55], v[54:55], s[6:7] op_sel_hi:[1,0]
	v_mul_f32_e64 v52, v52, s6
	v_mul_f32_e64 v53, v53, s6
	v_mul_f32_e64 v50, v50, s6
	v_mul_f32_e64 v51, v51, s6
	ds_read_b128 v[126:129], v209 offset:64512
	s_waitcnt lgkmcnt(5)
	v_mfma_f32_32x32x16_bf16 v[82:97], v[244:247], v[102:105], v[82:97]
	v_pk_mul_f32 v[48:49], v[48:49], s[6:7] op_sel_hi:[1,0]
	v_pk_mul_f32 v[46:47], v[46:47], s[6:7] op_sel_hi:[1,0]
	v_pk_mul_f32 v[44:45], v[44:45], s[6:7] op_sel_hi:[1,0]
	v_pk_mul_f32 v[42:43], v[42:43], s[6:7] op_sel_hi:[1,0]
	v_mul_f32_e64 v40, v40, s6
	ds_read_b128 v[236:239], v210 offset:8192
	s_waitcnt lgkmcnt(5)
	v_mfma_f32_32x32x16_bf16 v[82:97], v[168:171], v[98:101], v[82:97]
	v_mul_f32_e64 v41, v41, s6
	v_mul_f32_e64 v38, v38, s6
	v_mul_f32_e64 v39, v39, s6
	v_pk_mul_f32 v[36:37], v[36:37], s[6:7] op_sel_hi:[1,0]
	v_pk_mul_f32 v[34:35], v[34:35], s[6:7] op_sel_hi:[1,0]
	ds_read_b128 v[240:243], v210 offset:9216
	s_waitcnt lgkmcnt(5)
	v_mfma_f32_32x32x16_bf16 v[66:81], v[232:235], v[110:113], v[66:81]
	v_pk_mul_f32 v[32:33], v[32:33], s[6:7] op_sel_hi:[1,0]
	v_pk_mul_f32 v[30:31], v[30:31], s[6:7] op_sel_hi:[1,0]
	v_mul_f32_e64 v28, v28, s6
	v_mul_f32_e64 v29, v29, s6
	v_mul_f32_e64 v26, v26, s6
	ds_read_b128 v[244:247], v210 offset:10240
	s_waitcnt lgkmcnt(5)
	v_mfma_f32_32x32x16_bf16 v[66:81], v[118:121], v[106:109], v[66:81]
	v_mul_f32_e64 v27, v27, s6
	v_pk_mul_f32 v[24:25], v[24:25], s[6:7] op_sel_hi:[1,0]
	v_pk_mul_f32 v[22:23], v[22:23], s[6:7] op_sel_hi:[1,0]
	v_pk_mul_f32 v[20:21], v[20:21], s[6:7] op_sel_hi:[1,0]
	v_pk_mul_f32 v[18:19], v[18:19], s[6:7] op_sel_hi:[1,0]
	ds_read_b128 v[168:171], v210 offset:11264
	s_waitcnt lgkmcnt(5)
	v_mfma_f32_32x32x16_bf16 v[66:81], v[122:125], v[102:105], v[66:81]
	v_pk_mul_f32 v[16:17], v[16:17], s[6:7] op_sel_hi:[1,0]
	v_pk_mul_f32 v[14:15], v[14:15], s[6:7] op_sel_hi:[1,0]
	v_pk_mul_f32 v[12:13], v[12:13], s[6:7] op_sel_hi:[1,0]
	v_mul_f32_e64 v10, v10, s6
	v_mul_f32_e64 v11, v11, s6
	ds_read_b128 v[232:235], v210 offset:12288
	s_waitcnt lgkmcnt(5)
	v_mfma_f32_32x32x16_bf16 v[66:81], v[126:129], v[98:101], v[66:81]
	v_mul_f32_e64 v8, v8, s6
	v_mul_f32_e64 v9, v9, s6
	v_pk_mul_f32 v[6:7], v[6:7], s[6:7] op_sel_hi:[1,0]
	v_pk_mul_f32 v[4:5], v[4:5], s[6:7] op_sel_hi:[1,0]
	v_pk_mul_f32 v[2:3], v[2:3], s[6:7] op_sel_hi:[1,0]
	ds_read_b128 v[118:121], v210 offset:13312
	s_waitcnt lgkmcnt(5)
	v_mfma_f32_32x32x16_bf16 v[50:65], v[236:239], v[110:113], v[50:65]
	ds_read_b128 v[122:125], v210 offset:14336
	s_waitcnt lgkmcnt(5)
	v_mfma_f32_32x32x16_bf16 v[50:65], v[240:243], v[106:109], v[50:65]
	ds_read_b128 v[126:129], v210 offset:15360
	s_waitcnt lgkmcnt(5)
	v_mfma_f32_32x32x16_bf16 v[50:65], v[244:247], v[102:105], v[50:65]
	ds_read_b128 v[236:239], v210 offset:16384
	s_waitcnt lgkmcnt(5)
; __device__ __forceinline__ f32x16 mma32(bf16x8 a, bf16x8 b, f32x16 c) { return __builtin_amdgcn_mfma_f32_32x32x16_bf16(a, b, c, 0, 0, 0); }
; #define LDS_WAIT() asm volatile("s_waitcnt lgkmcnt(0)" ::: "memory")
; __device__ __forceinline__ void delta_scan_task(const P& p, int l, int s, int h, int sl, LAS unsigned char* ldsw, int lane) {
;     ...
; #pragma unroll
;         for (int d = 0; d < 4; ++d) {
; #pragma unroll
;             for (int reg = 0; reg < 16; ++reg) S[d][reg] *= dec;
; #pragma unroll
;             for (int ks = 0; ks < 4; ++ks) S[d] = mma32(FRAG16(bufB, 8 + d * 4 + ks, lane), ub[ks], S[d]);
;         }
;         LDS_WAIT();
;         if (SCAN_LOADERS) { if (lane == 0) FL[4] = (unsigned)n + 1u; } else delta_issue_B(p, chn, bufB, r, hh);
	v_mfma_f32_32x32x16_bf16 v[50:65], v[168:171], v[98:101], v[50:65]
	s_nop 7
	s_mov_b32 s4, 0x9000
	v_lshl_add_u64 v[114:115], v[192:193], 0, v[162:163]
	s_nop 2
	global_store_dword v[114:115], v82, off
	v_ashrrev_i32_e32 v115, 31, v162
	v_mov_b32_e32 v114, v162
	v_lshl_add_u64 v[114:115], v[192:193], 0, v[114:115]
	v_add_co_u32_e32 v116, vcc, s57, v114
	s_nop 0
	v_addc_co_u32_e32 v117, vcc, 0, v115, vcc
	v_add_co_u32_e32 v82, vcc, s97, v114
	global_store_dword v[116:117], v83, off offset:-4096
	global_store_dword v[116:117], v84, off
	v_addc_co_u32_e32 v83, vcc, 0, v115, vcc
	global_store_dword v[82:83], v85, off
	v_add_co_u32_e32 v82, vcc, s4, v114
	s_mov_b32 s4, 0x11000
	s_nop 0
	v_addc_co_u32_e32 v83, vcc, 0, v115, vcc
	global_store_dword v[82:83], v86, off offset:-4096
	global_store_dword v[82:83], v87, off
	v_add_co_u32_e32 v82, vcc, s96, v114
	s_nop 0
	v_addc_co_u32_e32 v83, vcc, 0, v115, vcc
	global_store_dword v[82:83], v88, off offset:-4096
	global_store_dword v[82:83], v89, off
	v_add_co_u32_e32 v82, vcc, s4, v114
	s_mov_b32 s4, 0x13000
	s_nop 0
	v_addc_co_u32_e32 v83, vcc, 0, v115, vcc
	global_store_dword v[82:83], v90, off offset:-4096
	global_store_dword v[82:83], v91, off
	v_add_co_u32_e32 v82, vcc, s4, v114
	s_mov_b32 s4, 0x19000
	s_nop 0
	v_addc_co_u32_e32 v83, vcc, 0, v115, vcc
	global_store_dword v[82:83], v92, off offset:-4096
	global_store_dword v[82:83], v93, off
	v_add_co_u32_e32 v82, vcc, s4, v114
	s_mov_b32 s4, 0x21000
	s_nop 0
	v_addc_co_u32_e32 v83, vcc, 0, v115, vcc
	global_store_dword v[82:83], v94, off offset:-4096
	global_store_dword v[82:83], v95, off
	v_add_co_u32_e32 v82, vcc, s16, v114
	s_nop 0
	v_addc_co_u32_e32 v83, vcc, 0, v115, vcc
	global_store_dword v[82:83], v96, off offset:-4096
	global_store_dword v[82:83], v97, off
	ds_read_b128 v[240:243], v210 offset:17408
	s_waitcnt lgkmcnt(5)
	v_mfma_f32_32x32x16_bf16 v[34:49], v[232:235], v[110:113], v[34:49]
	ds_read_b128 v[244:247], v210 offset:18432
	s_waitcnt lgkmcnt(5)
	v_mfma_f32_32x32x16_bf16 v[34:49], v[118:121], v[106:109], v[34:49]
	ds_read_b128 v[168:171], v210 offset:19456
	s_waitcnt lgkmcnt(5)
	v_mfma_f32_32x32x16_bf16 v[34:49], v[122:125], v[102:105], v[34:49]
	ds_read_b128 v[232:235], v210 offset:20480
	s_waitcnt lgkmcnt(5)
	v_mfma_f32_32x32x16_bf16 v[34:49], v[126:129], v[98:101], v[34:49]
	s_nop 7
	v_add_co_u32_e32 v82, vcc, s4, v114
	s_mov_b32 s4, 0x23000
	s_nop 0
	v_addc_co_u32_e32 v83, vcc, 0, v115, vcc
	s_nop 7
	global_store_dword v[82:83], v66, off offset:-4096
	global_store_dword v[82:83], v67, off
	v_add_co_u32_e32 v66, vcc, s4, v114
	s_mov_b32 s4, 0x29000
	s_nop 0
	v_addc_co_u32_e32 v67, vcc, 0, v115, vcc
	global_store_dword v[66:67], v68, off offset:-4096
	global_store_dword v[66:67], v69, off
	v_add_co_u32_e32 v66, vcc, s4, v114
	s_mov_b32 s4, 0x2b000
	s_nop 0
	v_addc_co_u32_e32 v67, vcc, 0, v115, vcc
	global_store_dword v[66:67], v70, off offset:-4096
	global_store_dword v[66:67], v71, off
	v_add_co_u32_e32 v66, vcc, s4, v114
	s_mov_b32 s4, 0x31000
	s_nop 0
	v_addc_co_u32_e32 v67, vcc, 0, v115, vcc
	global_store_dword v[66:67], v72, off offset:-4096
	global_store_dword v[66:67], v73, off
	v_add_co_u32_e32 v66, vcc, s4, v114
	s_mov_b32 s4, 0x33000
	s_nop 0
	v_addc_co_u32_e32 v67, vcc, 0, v115, vcc
	global_store_dword v[66:67], v74, off offset:-4096
	global_store_dword v[66:67], v75, off
	v_add_co_u32_e32 v66, vcc, s4, v114
	s_mov_b32 s4, 0x39000
	s_nop 0
	v_addc_co_u32_e32 v67, vcc, 0, v115, vcc
	global_store_dword v[66:67], v76, off offset:-4096
	global_store_dword v[66:67], v77, off
	v_add_co_u32_e32 v66, vcc, s4, v114
	s_mov_b32 s4, 0x3b000
	s_nop 0
	v_addc_co_u32_e32 v67, vcc, 0, v115, vcc
	global_store_dword v[66:67], v78, off offset:-4096
	global_store_dword v[66:67], v79, off
	v_add_co_u32_e32 v66, vcc, s4, v114
	s_nop 1
	v_addc_co_u32_e32 v67, vcc, 0, v115, vcc
	global_store_dword v[66:67], v80, off offset:-4096
	global_store_dword v[66:67], v81, off
	ds_read_b128 v[118:121], v210 offset:21504
	s_waitcnt lgkmcnt(5)
	v_mfma_f32_32x32x16_bf16 v[18:33], v[236:239], v[110:113], v[18:33]
	ds_read_b128 v[122:125], v210 offset:22528
	s_waitcnt lgkmcnt(5)
	v_mfma_f32_32x32x16_bf16 v[18:33], v[240:243], v[106:109], v[18:33]
	ds_read_b128 v[126:129], v210 offset:23552
	s_and_saveexec_b64 s[100:101], s[0:1]
	v_mov_b32_e32 v255, s34
	ds_write_b32 v163, v255 offset:13328
	s_or_b64 exec, exec, s[100:101]
	s_waitcnt lgkmcnt(6)
	v_mfma_f32_32x32x16_bf16 v[18:33], v[244:247], v[102:105], v[18:33]
	s_waitcnt lgkmcnt(5)
	v_mfma_f32_32x32x16_bf16 v[18:33], v[168:171], v[98:101], v[18:33]
	s_waitcnt lgkmcnt(4)
	v_mfma_f32_32x32x16_bf16 v[2:17], v[232:235], v[110:113], v[2:17]
	s_waitcnt lgkmcnt(3)
	v_mfma_f32_32x32x16_bf16 v[2:17], v[118:121], v[106:109], v[2:17]
	s_waitcnt lgkmcnt(2)
	v_mfma_f32_32x32x16_bf16 v[2:17], v[122:125], v[102:105], v[2:17]
	s_waitcnt lgkmcnt(1)
	v_mfma_f32_32x32x16_bf16 v[2:17], v[126:129], v[98:101], v[2:17]
	s_and_saveexec_b64 s[6:7], s[0:1]
	s_cbranch_execz .LBB0_1479
	s_branch .LBB0_1479

; __device__ __forceinline__ f32x16 mma32(bf16x8 a, bf16x8 b, f32x16 c) { return __builtin_amdgcn_mfma_f32_32x32x16_bf16(a, b, c, 0, 0, 0); }
; #define LDS_WAIT() asm volatile("s_waitcnt lgkmcnt(0)" ::: "memory")
; __device__ __forceinline__ void gla_scan_task(const P& p, int l, int s, int h, int sl, LAS unsigned char* ldsw, int lane) {
;     ...
; #pragma unroll
;         for (int d = 0; d < 4; ++d) {
; #pragma unroll
;             for (int ks = 0; ks < 4; ++ks) S[d] = mma32(FRAG16(bufB, d * 4 + ks, lane), vb[ks], S[d]);
; #pragma unroll
;             for (int g = 0; g < 4; ++g) { const f32x4v dc = FRAGF4(bufB, 16 + d * 4 + g, lane); S[d][4 * g] *= dc.x; S[d][4 * g + 1] *= dc.y; S[d][4 * g + 2] *= dc.z; S[d][4 * g + 3] *= dc.w; }
;         }
;         LDS_WAIT();
;         if (SCAN_LOADERS) { if (lane == 0) FL[4] = (unsigned)n + 1u; } else gla_issue_B(p, chn, bufB, r, hh);
.LBB0_1556:
	s_waitcnt lgkmcnt(0)
	v_add_u32_e32 v173, 0xf000, v209
	ds_read_b128 v[236:239], v209 offset:45056
	ds_read_b128 v[240:243], v209 offset:46080
	ds_read_b128 v[244:247], v209 offset:47104
	ds_read_b128 v[168:171], v209 offset:48128
	ds_read_b128 v[212:215], v209 offset:49152
	ds_read_b128 v[216:219], v209 offset:50176
	s_waitcnt lgkmcnt(5)
	v_mfma_f32_32x32x16_bf16 v[50:65], v[236:239], v[94:97], v[50:65]
	ds_read_b128 v[220:223], v209 offset:51200
	s_waitcnt lgkmcnt(5)
	v_mfma_f32_32x32x16_bf16 v[50:65], v[240:243], v[90:93], v[50:65]
	ds_read_b128 v[224:227], v209 offset:52224
	s_waitcnt lgkmcnt(5)
	v_mfma_f32_32x32x16_bf16 v[50:65], v[244:247], v[86:89], v[50:65]
	ds_read_b128 v[228:231], v209 offset:53248
	s_waitcnt lgkmcnt(5)
	v_mfma_f32_32x32x16_bf16 v[50:65], v[168:171], v[82:85], v[50:65]
	ds_read_b128 v[98:101], v173 offset:0
	ds_read_b128 v[74:77], v173 offset:1024
	ds_read_b128 v[70:73], v173 offset:2048
	ds_read_b128 v[66:69], v173 offset:3072
	ds_read_b128 v[232:235], v209 offset:54272
	s_waitcnt lgkmcnt(9)
	v_mfma_f32_32x32x16_bf16 v[34:49], v[212:215], v[94:97], v[34:49]
	ds_read_b128 v[236:239], v209 offset:55296
	s_waitcnt lgkmcnt(9)
	v_mfma_f32_32x32x16_bf16 v[34:49], v[216:219], v[90:93], v[34:49]
	ds_read_b128 v[240:243], v209 offset:56320
	s_waitcnt lgkmcnt(9)
	v_mfma_f32_32x32x16_bf16 v[34:49], v[220:223], v[86:89], v[34:49]
	ds_read_b128 v[244:247], v209 offset:57344
	s_waitcnt lgkmcnt(9)
	v_mfma_f32_32x32x16_bf16 v[34:49], v[224:227], v[82:85], v[34:49]
	ds_read_b128 v[110:113], v173 offset:4096
	ds_read_b128 v[106:109], v173 offset:5120
	ds_read_b128 v[102:105], v173 offset:6144
	ds_read_b128 v[78:81], v173 offset:7168
	ds_read_b128 v[168:171], v209 offset:58368
	s_waitcnt lgkmcnt(13)
	v_mfma_f32_32x32x16_bf16 v[18:33], v[228:231], v[94:97], v[18:33]
	ds_read_b128 v[212:215], v209 offset:59392
	s_waitcnt lgkmcnt(9)
	v_mfma_f32_32x32x16_bf16 v[18:33], v[232:235], v[90:93], v[18:33]
	ds_read_b128 v[216:219], v209 offset:60416
	s_waitcnt lgkmcnt(9)
	v_mfma_f32_32x32x16_bf16 v[18:33], v[236:239], v[86:89], v[18:33]
	s_waitcnt lgkmcnt(8)
	v_mfma_f32_32x32x16_bf16 v[18:33], v[240:243], v[82:85], v[18:33]
	ds_read_b128 v[126:129], v173 offset:8192
	ds_read_b128 v[122:125], v173 offset:9216
	ds_read_b128 v[118:121], v173 offset:10240
	ds_read_b128 v[114:117], v173 offset:11264
	s_waitcnt lgkmcnt(11)
	v_mfma_f32_32x32x16_bf16 v[2:17], v[244:247], v[94:97], v[2:17]
	s_waitcnt lgkmcnt(6)
	v_mfma_f32_32x32x16_bf16 v[2:17], v[168:171], v[90:93], v[2:17]
	s_waitcnt lgkmcnt(5)
	v_mfma_f32_32x32x16_bf16 v[2:17], v[212:215], v[86:89], v[2:17]
	s_waitcnt lgkmcnt(4)
	v_mfma_f32_32x32x16_bf16 v[2:17], v[216:219], v[82:85], v[2:17]
	ds_read_b128 v[90:93], v173 offset:12288
	ds_read_b128 v[94:97], v173 offset:13312
	ds_read_b128 v[82:85], v173 offset:14336
	ds_read_b128 v[86:89], v173 offset:15360
	s_and_saveexec_b64 s[8:9], s[0:1]
	s_cbranch_execz .LBB0_1520
	v_mov_b32_e32 v132, s7
	ds_write_b32 v163, v132 offset:13328
	s_branch .LBB0_1520
